# expert GEMMs: the scale-1.0 block-scaled fp8 MFMA replaced by the plain v_mfma_f32_16x16x128_f8f6f4 (same fp8 operands, same f32 accumulate, no scale operands)
# speedup vs baseline: 1.0058x; 1.0058x over previous
; #define PG8_STAGE(bufoff, gbase, voff) do { _Pragma("unroll") for (int _i = 0; _i < 2; ++_i) \
;         __builtin_amdgcn_global_load_lds((const unsigned*)((const char*)(gbase) + (voff)[_i]), (PG8_LAS unsigned*)(lds + (bufoff) + ldsw + _i * 8192), 16, 0, 0); } while (0)
; #define PG8_LDA(dst, b, h) do { _Pragma("unroll") for (int m = 0; m < 4; ++m) _Pragma("unroll") for (int k = 0; k < 2; ++k) dst[m][k] = *(const PG8_LAS bf16x8*)(lds + PG8_SA(b, h) + aoff + m * 2048 + k * 1024); } while (0)
; #define PG8_WAIT_V(n) asm volatile("s_waitcnt vmcnt(" #n ")" ::: "memory")
; #define PG8_WAIT_VR(relax) do { if (relax) asm volatile("s_waitcnt vmcnt(%0)" :: "n"(8 + Epi::NST) : "memory"); else asm volatile("s_waitcnt vmcnt(8)" ::: "memory"); } while (0)
; #define PG8_WAIT_L(n) asm volatile("s_waitcnt lgkmcnt(" #n ")" ::: "memory")
; #define PG8_BAR __builtin_amdgcn_s_barrier()
; #define PG8_SCHED __builtin_amdgcn_sched_barrier(0)
; template <class Epi, class Sched, bool ALIGN_EPI = false, bool SP2 = false, bool F8 = false, bool GATHER = false>
; __device__ __forceinline__ void gemm_phase(PG8_LAS unsigned char* lds, const Gemm g, const Sched& S, const Epi& E, const int tid_in) {
;     ...
;             PG8_WAIT_VR(relax); PG8_WAIT_L(0); PG8_BAR; PG8_MMA(0, 0, At, B0); PG8_MMA(0, 1, At, B1); PG8_BAR; PG8_SCHED;
;             PG8_LDA(At, 1, 1); PG8_STAGE(PG8_SB(1, 0), b3, voffB); PG8_STAGE(PG8_SB(1, 1), b3 + hstep, voffB); PG8_STAGE(PG8_SA(1, 0), a3, vA0s);
;             PG8_WAIT_V(8); PG8_WAIT_L(0); PG8_BAR; PG8_MMA(1, 0, At, B0); PG8_MMA(1, 1, At, B1); PG8_BAR; PG8_SCHED;
.LBB0_1001:
	s_waitcnt lgkmcnt(0)
	v_mov_b32_e32 v223, v16
	v_mov_b32_e32 v221, v16
	v_lshl_add_u64 v[196:197], s[62:63], 0, v[222:223]
	v_lshl_add_u64 v[220:221], s[62:63], 0, v[220:221]
	s_barrier
	s_setprio 1
	s_waitcnt lgkmcnt(0)
	v_mfma_f32_16x16x128_f8f6f4 v[192:195], v[26:33], v[58:65], v[192:195]
	v_mfma_f32_16x16x128_f8f6f4 v[188:191], v[18:25], v[58:65], v[188:191]
	v_mfma_f32_16x16x128_f8f6f4 v[176:179], v[26:33], v[50:57], v[176:179]
	v_mfma_f32_16x16x128_f8f6f4 v[172:175], v[18:25], v[50:57], v[172:175]
	v_mfma_f32_16x16x128_f8f6f4 v[160:163], v[26:33], v[42:49], v[160:163]
	v_mfma_f32_16x16x128_f8f6f4 v[156:159], v[18:25], v[42:49], v[156:159]
	v_mfma_f32_16x16x128_f8f6f4 v[144:147], v[26:33], v[34:41], v[144:147]
	v_mfma_f32_16x16x128_f8f6f4 v[140:143], v[18:25], v[34:41], v[140:143]
	s_setprio 0
	s_setprio 1
	v_mfma_f32_16x16x128_f8f6f4 v[184:187], v[8:15], v[58:65], v[184:187]
	v_mfma_f32_16x16x128_f8f6f4 v[180:183], v[0:7], v[58:65], v[180:183]
	v_mfma_f32_16x16x128_f8f6f4 v[168:171], v[8:15], v[50:57], v[168:171]
	v_mfma_f32_16x16x128_f8f6f4 v[164:167], v[0:7], v[50:57], v[164:167]
	v_mfma_f32_16x16x128_f8f6f4 v[152:155], v[8:15], v[42:49], v[152:155]
	v_mfma_f32_16x16x128_f8f6f4 v[148:151], v[0:7], v[42:49], v[148:151]
	v_mfma_f32_16x16x128_f8f6f4 v[136:139], v[8:15], v[34:41], v[136:139]
	v_mfma_f32_16x16x128_f8f6f4 v[132:135], v[0:7], v[34:41], v[132:135]
	s_setprio 0
	s_barrier
	s_mov_b32 m0, s84
	v_lshl_add_u64 v[222:223], v[224:225], 0, s[6:7]
	s_add_u32 s42, s60, 0x20080
	ds_read_b128 v[34:37], v231 offset:49152
	ds_read_b128 v[38:41], v231 offset:50176
	ds_read_b128 v[42:45], v231 offset:51200
	ds_read_b128 v[46:49], v231 offset:52224
	ds_read_b128 v[50:53], v231 offset:53248
	ds_read_b128 v[54:57], v231 offset:54272
	ds_read_b128 v[58:61], v231 offset:55296
	ds_read_b128 v[62:65], v231 offset:56320
	global_load_lds_dwordx4 v[222:223], off
	v_lshl_add_u64 v[222:223], v[226:227], 0, s[6:7]
	s_mov_b32 m0, s85
	s_addc_u32 s43, s61, 0
	global_load_lds_dwordx4 v[222:223], off
	v_lshl_add_u64 v[222:223], s[42:43], 0, v[202:203]
	s_mov_b32 m0, s88
	v_lshl_add_u64 v[196:197], v[196:197], 0, s[6:7]
	global_load_lds_dwordx4 v[222:223], off
	v_lshl_add_u64 v[222:223], s[42:43], 0, v[204:205]
	s_mov_b32 m0, s89
	s_nop 0
	global_load_lds_dwordx4 v[222:223], off
	s_mov_b32 m0, s86
	s_nop 0
	global_load_lds_dwordx4 v[196:197], off
	v_lshl_add_u64 v[196:197], v[220:221], 0, s[6:7]
	s_mov_b32 m0, s87
	s_nop 0
	global_load_lds_dwordx4 v[196:197], off
	s_waitcnt vmcnt(8)
	s_waitcnt lgkmcnt(0)
	s_barrier
	s_setprio 1
	s_waitcnt lgkmcnt(0)
	v_mfma_f32_16x16x128_f8f6f4 v[128:131], v[26:33], v[34:41], v[128:131]
	v_mfma_f32_16x16x128_f8f6f4 v[124:127], v[18:25], v[34:41], v[124:127]
	v_mfma_f32_16x16x128_f8f6f4 v[112:115], v[26:33], v[42:49], v[112:115]
	v_mfma_f32_16x16x128_f8f6f4 v[108:111], v[18:25], v[42:49], v[108:111]
	v_mfma_f32_16x16x128_f8f6f4 v[96:99], v[26:33], v[50:57], v[96:99]
	v_mfma_f32_16x16x128_f8f6f4 v[92:95], v[18:25], v[50:57], v[92:95]
	v_mfma_f32_16x16x128_f8f6f4 v[80:83], v[26:33], v[58:65], v[80:83]
	v_mfma_f32_16x16x128_f8f6f4 v[76:79], v[18:25], v[58:65], v[76:79]
	s_setprio 0
	s_setprio 1
	v_mfma_f32_16x16x128_f8f6f4 v[120:123], v[8:15], v[34:41], v[120:123]
	v_mfma_f32_16x16x128_f8f6f4 v[116:119], v[0:7], v[34:41], v[116:119]
	v_mfma_f32_16x16x128_f8f6f4 v[104:107], v[8:15], v[42:49], v[104:107]
	v_mfma_f32_16x16x128_f8f6f4 v[100:103], v[0:7], v[42:49], v[100:103]
	v_mfma_f32_16x16x128_f8f6f4 v[88:91], v[8:15], v[50:57], v[88:91]
	v_mfma_f32_16x16x128_f8f6f4 v[84:87], v[0:7], v[50:57], v[84:87]
	v_mfma_f32_16x16x128_f8f6f4 v[72:75], v[8:15], v[58:65], v[72:75]
	v_mfma_f32_16x16x128_f8f6f4 v[68:71], v[0:7], v[58:65], v[68:71]
	s_setprio 0
	s_barrier
	s_add_i32 s55, s55, 2
	s_add_u32 s36, s36, 0x100
	s_addc_u32 s37, s37, 0
	s_cmp_gt_u32 s55, 5
	s_cbranch_scc1 .LBB0_1016

; #define PG8_STAGE(bufoff, gbase, voff) do { _Pragma("unroll") for (int _i = 0; _i < 2; ++_i) \
;         __builtin_amdgcn_global_load_lds((const unsigned*)((const char*)(gbase) + (voff)[_i]), (PG8_LAS unsigned*)(lds + (bufoff) + ldsw + _i * 8192), 16, 0, 0); } while (0)
; #define PG8_LDA(dst, b, h) do { _Pragma("unroll") for (int m = 0; m < 4; ++m) _Pragma("unroll") for (int k = 0; k < 2; ++k) dst[m][k] = *(const PG8_LAS bf16x8*)(lds + PG8_SA(b, h) + aoff + m * 2048 + k * 1024); } while (0)
; #define PG8_LDB(dst, b, h) do { _Pragma("unroll") for (int n = 0; n < 2; ++n) _Pragma("unroll") for (int k = 0; k < 2; ++k) dst[n][k] = *(const PG8_LAS bf16x8*)(lds + PG8_SB(b, h) + boff + n * 2048 + k * 1024); } while (0)
; #define PG8_WAIT_VR(relax) do { if (relax) asm volatile("s_waitcnt vmcnt(%0)" :: "n"(8 + Epi::NST) : "memory"); else asm volatile("s_waitcnt vmcnt(8)" ::: "memory"); } while (0)
; #define PG8_WAIT_L(n) asm volatile("s_waitcnt lgkmcnt(" #n ")" ::: "memory")
; #define PG8_BAR __builtin_amdgcn_s_barrier()
; #define PG8_SCHED __builtin_amdgcn_sched_barrier(0)
; template <class Epi, class Sched, bool ALIGN_EPI = false, bool SP2 = false, bool F8 = false, bool GATHER = false>
; __device__ __forceinline__ void gemm_phase(PG8_LAS unsigned char* lds, const Gemm g, const Sched& S, const Epi& E, const int tid_in) {
;     ...
;             const char* a1 = cA + (size_t)(t + 1) * kstep;
;             const char* a2 = last ? nA : cA + (size_t)(t + 2) * kstep; const char* b2 = last ? nB : cB + (size_t)(t + 2) * kstep;
;             const char* a3 = a2 + kstep; const char* b3 = b2 + kstep;
;             if (last && has_next) S.a_ready(nxt);
;             const bool relax = SP2 && ALIGN_EPI && t == 0 && ui > 0;
;             if constexpr (SP2) {
;             PG8_LDB(B0, 0, 0); PG8_LDB(B1, 0, 1); PG8_SCHED; PG8_LDA(At, 0, 0); if (!relax) PG8_STAGE(PG8_SA(1, 1), a1 + hstepA, vA1c);
;             PG8_WAIT_VR(relax); PG8_WAIT_L(0); PG8_BAR; PG8_MMA(0, 0, At, B0); PG8_MMA(0, 1, At, B1); PG8_BAR; PG8_SCHED;
;             PG8_LDA(At, 0, 1); PG8_STAGE(PG8_SB(0, 0), b2, voffB); PG8_STAGE(PG8_SB(0, 1), b2 + hstep, voffB); PG8_STAGE(PG8_SA(0, 0), a2, vA0s);
.LBB0_1008:
	s_xor_b64 s[64:65], s[42:43], -1
	s_add_u32 s42, s16, s36
	s_addc_u32 s43, s17, s37
	s_add_u32 s62, s42, 0xcf000100
	s_addc_u32 s63, s43, 0
	s_add_u32 s66, s35, s36
	s_addc_u32 s67, s53, s37
	s_cmpk_eq_i32 s36, 0x300
	s_cselect_b64 s[42:43], -1, 0
	s_waitcnt lgkmcnt(0)
	s_and_b64 s[60:61], s[42:43], exec
	v_cndmask_b32_e64 v220, v210, v234, s[42:43]
	v_cndmask_b32_e64 v222, v208, v215, s[42:43]
	s_cselect_b32 s63, s31, s63
	s_cselect_b32 s62, s30, s62
	s_cselect_b32 s61, s3, s67
	s_cselect_b32 s60, s34, s66
	s_barrier
	s_setprio 1
	s_waitcnt lgkmcnt(0)
	v_mfma_f32_16x16x128_f8f6f4 v[192:195], v[26:33], v[58:65], v[192:195]
	v_mfma_f32_16x16x128_f8f6f4 v[188:191], v[18:25], v[58:65], v[188:191]
	v_mfma_f32_16x16x128_f8f6f4 v[176:179], v[26:33], v[50:57], v[176:179]
	v_mfma_f32_16x16x128_f8f6f4 v[172:175], v[18:25], v[50:57], v[172:175]
	v_mfma_f32_16x16x128_f8f6f4 v[160:163], v[26:33], v[42:49], v[160:163]
	v_mfma_f32_16x16x128_f8f6f4 v[156:159], v[18:25], v[42:49], v[156:159]
	v_mfma_f32_16x16x128_f8f6f4 v[144:147], v[26:33], v[34:41], v[144:147]
	v_mfma_f32_16x16x128_f8f6f4 v[140:143], v[18:25], v[34:41], v[140:143]
	s_setprio 0
	s_setprio 1
	v_mfma_f32_16x16x128_f8f6f4 v[184:187], v[8:15], v[58:65], v[184:187]
	v_mfma_f32_16x16x128_f8f6f4 v[180:183], v[0:7], v[58:65], v[180:183]
	v_mfma_f32_16x16x128_f8f6f4 v[168:171], v[8:15], v[50:57], v[168:171]
	v_mfma_f32_16x16x128_f8f6f4 v[164:167], v[0:7], v[50:57], v[164:167]
	v_mfma_f32_16x16x128_f8f6f4 v[152:155], v[8:15], v[42:49], v[152:155]
	v_mfma_f32_16x16x128_f8f6f4 v[148:151], v[0:7], v[42:49], v[148:151]
	v_mfma_f32_16x16x128_f8f6f4 v[136:139], v[8:15], v[34:41], v[136:139]
	v_mfma_f32_16x16x128_f8f6f4 v[132:135], v[0:7], v[34:41], v[132:135]
	s_setprio 0
	s_barrier
	s_mov_b32 m0, s77
	v_lshl_add_u64 v[224:225], s[60:61], 0, v[202:203]
	s_add_u32 s66, s60, 0x20000
	ds_read_b128 v[58:61], v231 offset:16384
	ds_read_b128 v[62:65], v231 offset:17408
	ds_read_b128 v[50:53], v231 offset:18432
	ds_read_b128 v[54:57], v231 offset:19456
	ds_read_b128 v[42:45], v231 offset:20480
	ds_read_b128 v[46:49], v231 offset:21504
	ds_read_b128 v[34:37], v231 offset:22528
	ds_read_b128 v[38:41], v231 offset:23552
	global_load_lds_dwordx4 v[224:225], off
	v_lshl_add_u64 v[226:227], s[60:61], 0, v[204:205]
	s_mov_b32 m0, s78
	s_addc_u32 s67, s61, 0
	global_load_lds_dwordx4 v[226:227], off
	v_lshl_add_u64 v[196:197], s[66:67], 0, v[202:203]
	s_mov_b32 m0, s79
	s_and_b64 vcc, exec, s[64:65]
	global_load_lds_dwordx4 v[196:197], off
	v_lshl_add_u64 v[196:197], s[66:67], 0, v[204:205]
	s_mov_b32 m0, s80
	s_mov_b64 s[66:67], -1
	global_load_lds_dwordx4 v[196:197], off
	s_mov_b32 m0, s76
	s_nop 0
	global_load_lds_dwordx4 v222, s[62:63]
	s_mov_b32 m0, s81
	s_nop 0
	global_load_lds_dwordx4 v220, s[62:63]
	s_cbranch_vccz .LBB0_1010
	s_waitcnt vmcnt(8)
	s_mov_b64 s[66:67], 0

; #define PG8_STAGE(bufoff, gbase, voff) do { _Pragma("unroll") for (int _i = 0; _i < 2; ++_i) \
;         __builtin_amdgcn_global_load_lds((const unsigned*)((const char*)(gbase) + (voff)[_i]), (PG8_LAS unsigned*)(lds + (bufoff) + ldsw + _i * 8192), 16, 0, 0); } while (0)
; #define PG8_LDA(dst, b, h) do { _Pragma("unroll") for (int m = 0; m < 4; ++m) _Pragma("unroll") for (int k = 0; k < 2; ++k) dst[m][k] = *(const PG8_LAS bf16x8*)(lds + PG8_SA(b, h) + aoff + m * 2048 + k * 1024); } while (0)
; #define PG8_LDB(dst, b, h) do { _Pragma("unroll") for (int n = 0; n < 2; ++n) _Pragma("unroll") for (int k = 0; k < 2; ++k) dst[n][k] = *(const PG8_LAS bf16x8*)(lds + PG8_SB(b, h) + boff + n * 2048 + k * 1024); } while (0)
; #define PG8_WAIT_VR(relax) do { if (relax) asm volatile("s_waitcnt vmcnt(%0)" :: "n"(8 + Epi::NST) : "memory"); else asm volatile("s_waitcnt vmcnt(8)" ::: "memory"); } while (0)
; #define PG8_WAIT_L(n) asm volatile("s_waitcnt lgkmcnt(" #n ")" ::: "memory")
; #define PG8_BAR __builtin_amdgcn_s_barrier()
; #define PG8_SCHED __builtin_amdgcn_sched_barrier(0)
; template <class Epi, class Sched, bool ALIGN_EPI = false, bool SP2 = false, bool F8 = false, bool GATHER = false>
; __device__ __forceinline__ void gemm_phase(PG8_LAS unsigned char* lds, const Gemm g, const Sched& S, const Epi& E, const int tid_in) {
;     ...
;                 if (last) { vA0s[0] = ga_nxt[0][0]; vA0s[1] = ga_nxt[0][1]; vA1s[0] = ga_nxt[1][0]; vA1s[1] = ga_nxt[1][1]; }
;                 else { vA0s[0] = ga_cur[0][0]; vA0s[1] = ga_cur[0][1]; vA1s[0] = ga_cur[1][0]; vA1s[1] = ga_cur[1][1]; }
;     ...
;             PG8_WAIT_VR(relax); PG8_WAIT_L(0); PG8_BAR; PG8_MMA(1, 0, At, B0); PG8_MMA(1, 1, At, B1); PG8_BAR; PG8_SCHED;
;             PG8_LDB(B0, 1, 0); PG8_LDB(B1, 1, 1); PG8_SCHED; PG8_LDA(At, 1, 0); PG8_STAGE(PG8_SA(0, 1), a2 + hstepA, vA1s);
.LBB0_1012:
	s_waitcnt lgkmcnt(0)
	v_cndmask_b32_e64 v196, v214, v232, s[42:43]
	v_cndmask_b32_e64 v197, v212, v213, s[42:43]
	s_barrier
	s_setprio 1
	s_waitcnt lgkmcnt(0)
	v_mfma_f32_16x16x128_f8f6f4 v[128:131], v[26:33], v[58:65], v[128:131]
	v_mfma_f32_16x16x128_f8f6f4 v[124:127], v[18:25], v[58:65], v[124:127]
	v_mfma_f32_16x16x128_f8f6f4 v[112:115], v[26:33], v[50:57], v[112:115]
	v_mfma_f32_16x16x128_f8f6f4 v[108:111], v[18:25], v[50:57], v[108:111]
	v_mfma_f32_16x16x128_f8f6f4 v[96:99], v[26:33], v[42:49], v[96:99]
	v_mfma_f32_16x16x128_f8f6f4 v[92:95], v[18:25], v[42:49], v[92:95]
	v_mfma_f32_16x16x128_f8f6f4 v[80:83], v[26:33], v[34:41], v[80:83]
	v_mfma_f32_16x16x128_f8f6f4 v[76:79], v[18:25], v[34:41], v[76:79]
	s_setprio 0
	s_setprio 1
	v_mfma_f32_16x16x128_f8f6f4 v[120:123], v[8:15], v[58:65], v[120:123]
	v_mfma_f32_16x16x128_f8f6f4 v[116:119], v[0:7], v[58:65], v[116:119]
	v_mfma_f32_16x16x128_f8f6f4 v[104:107], v[8:15], v[50:57], v[104:107]
	v_mfma_f32_16x16x128_f8f6f4 v[100:103], v[0:7], v[50:57], v[100:103]
	v_mfma_f32_16x16x128_f8f6f4 v[88:91], v[8:15], v[42:49], v[88:91]
	v_mfma_f32_16x16x128_f8f6f4 v[84:87], v[0:7], v[42:49], v[84:87]
	v_mfma_f32_16x16x128_f8f6f4 v[72:75], v[8:15], v[34:41], v[72:75]
	v_mfma_f32_16x16x128_f8f6f4 v[68:71], v[0:7], v[34:41], v[68:71]
	s_setprio 0
	s_barrier
	v_add_u32_e32 v0, 0x18000, v249
	v_add_u32_e32 v4, 0x1c000, v249
	ds_read_b128 v[26:29], v0
	ds_read_b128 v[30:33], v0 offset:1024
	ds_read_b128 v[18:21], v0 offset:2048
	ds_read_b128 v[22:25], v0 offset:3072
	ds_read_b128 v[8:11], v4
	ds_read_b128 v[12:15], v4 offset:1024
	ds_read_b128 v[0:3], v4 offset:2048
	ds_read_b128 v[4:7], v4 offset:3072
	s_mov_b32 m0, s82
	ds_read_b128 v[58:61], v231 offset:32768
	ds_read_b128 v[62:65], v231 offset:33792
	ds_read_b128 v[50:53], v231 offset:34816
	ds_read_b128 v[54:57], v231 offset:35840
	ds_read_b128 v[42:45], v231 offset:36864
	ds_read_b128 v[46:49], v231 offset:37888
	ds_read_b128 v[34:37], v231 offset:38912
	ds_read_b128 v[38:41], v231 offset:39936
	global_load_lds_dwordx4 v197, s[62:63]
	s_mov_b32 m0, s83
	s_mov_b64 s[42:43], -1
	global_load_lds_dwordx4 v196, s[62:63]
	s_and_b64 vcc, exec, s[64:65]
	s_mov_b32 s66, s27
	s_mov_b32 s67, s24
	s_cbranch_vccz .LBB0_1014
	s_waitcnt vmcnt(8)
	s_mov_b64 s[42:43], 0

; #define PG8_STAGE(bufoff, gbase, voff) do { _Pragma("unroll") for (int _i = 0; _i < 2; ++_i) \
;         __builtin_amdgcn_global_load_lds((const unsigned*)((const char*)(gbase) + (voff)[_i]), (PG8_LAS unsigned*)(lds + (bufoff) + ldsw + _i * 8192), 16, 0, 0); } while (0)
; #define PG8_LDA(dst, b, h) do { _Pragma("unroll") for (int m = 0; m < 4; ++m) _Pragma("unroll") for (int k = 0; k < 2; ++k) dst[m][k] = *(const PG8_LAS bf16x8*)(lds + PG8_SA(b, h) + aoff + m * 2048 + k * 1024); } while (0)
; #define PG8_WAIT_V(n) asm volatile("s_waitcnt vmcnt(" #n ")" ::: "memory")
; #define PG8_WAIT_VR(relax) do { if (relax) asm volatile("s_waitcnt vmcnt(%0)" :: "n"(8 + Epi::NST) : "memory"); else asm volatile("s_waitcnt vmcnt(8)" ::: "memory"); } while (0)
; #define PG8_WAIT_L(n) asm volatile("s_waitcnt lgkmcnt(" #n ")" ::: "memory")
; #define PG8_BAR __builtin_amdgcn_s_barrier()
; #define PG8_SCHED __builtin_amdgcn_sched_barrier(0)
; template <class Epi, class Sched, bool ALIGN_EPI = false, bool SP2 = false, bool F8 = false, bool GATHER = false>
; __device__ __forceinline__ void gemm_phase(PG8_LAS unsigned char* lds, const Gemm g, const Sched& S, const Epi& E, const int tid_in) {
;     ...
;             PG8_WAIT_VR(relax); PG8_WAIT_L(0); PG8_BAR; PG8_MMA(0, 0, At, B0); PG8_MMA(0, 1, At, B1); PG8_BAR; PG8_SCHED;
;             PG8_LDA(At, 1, 1); PG8_STAGE(PG8_SB(1, 0), b3, voffB); PG8_STAGE(PG8_SB(1, 1), b3 + hstep, voffB); PG8_STAGE(PG8_SA(1, 0), a3, vA0s);
;             PG8_WAIT_V(8); PG8_WAIT_L(0); PG8_BAR; PG8_MMA(1, 0, At, B0); PG8_MMA(1, 1, At, B1); PG8_BAR; PG8_SCHED;
.LBB0_1109:
	s_waitcnt lgkmcnt(0)
	s_barrier
	s_setprio 1
	s_waitcnt lgkmcnt(0)
	v_mfma_f32_16x16x128_f8f6f4 v[192:195], v[26:33], v[58:65], v[192:195]
	v_mfma_f32_16x16x128_f8f6f4 v[188:191], v[18:25], v[58:65], v[188:191]
	v_mfma_f32_16x16x128_f8f6f4 v[184:187], v[26:33], v[50:57], v[184:187]
	v_mfma_f32_16x16x128_f8f6f4 v[180:183], v[18:25], v[50:57], v[180:183]
	v_mfma_f32_16x16x128_f8f6f4 v[160:163], v[26:33], v[42:49], v[160:163]
	v_mfma_f32_16x16x128_f8f6f4 v[156:159], v[18:25], v[42:49], v[156:159]
	v_mfma_f32_16x16x128_f8f6f4 v[152:155], v[26:33], v[34:41], v[152:155]
	v_mfma_f32_16x16x128_f8f6f4 v[148:151], v[18:25], v[34:41], v[148:151]
	s_setprio 0
	s_setprio 1
	v_mfma_f32_16x16x128_f8f6f4 v[176:179], v[8:15], v[58:65], v[176:179]
	v_mfma_f32_16x16x128_f8f6f4 v[172:175], v[0:7], v[58:65], v[172:175]
	v_mfma_f32_16x16x128_f8f6f4 v[168:171], v[8:15], v[50:57], v[168:171]
	v_mfma_f32_16x16x128_f8f6f4 v[164:167], v[0:7], v[50:57], v[164:167]
	v_mfma_f32_16x16x128_f8f6f4 v[144:147], v[8:15], v[42:49], v[144:147]
	v_mfma_f32_16x16x128_f8f6f4 v[140:143], v[0:7], v[42:49], v[140:143]
	v_mfma_f32_16x16x128_f8f6f4 v[136:139], v[8:15], v[34:41], v[136:139]
	v_mfma_f32_16x16x128_f8f6f4 v[132:135], v[0:7], v[34:41], v[132:135]
	s_setprio 0
	s_barrier
	s_mov_b32 m0, s83
	v_lshl_add_u64 v[196:197], v[218:219], 0, s[6:7]
	s_add_u32 s62, s62, 0x20080
	ds_read_b128 v[34:37], v242 offset:49152
	ds_read_b128 v[38:41], v242 offset:50176
	ds_read_b128 v[42:45], v242 offset:51200
	ds_read_b128 v[46:49], v242 offset:52224
	ds_read_b128 v[50:53], v242 offset:53248
	ds_read_b128 v[54:57], v242 offset:54272
	ds_read_b128 v[58:61], v242 offset:55296
	ds_read_b128 v[62:65], v242 offset:56320
	global_load_lds_dwordx4 v[196:197], off
	v_lshl_add_u64 v[196:197], v[220:221], 0, s[6:7]
	s_mov_b32 m0, s84
	s_addc_u32 s63, s63, 0
	global_load_lds_dwordx4 v[196:197], off
	v_lshl_add_u64 v[196:197], s[62:63], 0, v[204:205]
	s_mov_b32 m0, s87
	s_nop 0
	global_load_lds_dwordx4 v[196:197], off
	v_lshl_add_u64 v[196:197], s[62:63], 0, v[208:209]
	s_mov_b32 m0, s4
	s_nop 0
	global_load_lds_dwordx4 v[196:197], off
	v_lshl_add_u64 v[196:197], v[222:223], 0, s[6:7]
	s_mov_b32 m0, s85
	s_nop 0
	global_load_lds_dwordx4 v[196:197], off
	v_lshl_add_u64 v[196:197], v[224:225], 0, s[6:7]
	s_mov_b32 m0, s86
	s_nop 0
	global_load_lds_dwordx4 v[196:197], off
	s_waitcnt vmcnt(8)
	s_waitcnt lgkmcnt(0)
	s_barrier
	s_setprio 1
	s_waitcnt lgkmcnt(0)
	v_mfma_f32_16x16x128_f8f6f4 v[128:131], v[26:33], v[34:41], v[128:131]
	v_mfma_f32_16x16x128_f8f6f4 v[124:127], v[18:25], v[34:41], v[124:127]
	v_mfma_f32_16x16x128_f8f6f4 v[112:115], v[26:33], v[42:49], v[112:115]
	v_mfma_f32_16x16x128_f8f6f4 v[108:111], v[18:25], v[42:49], v[108:111]
	v_mfma_f32_16x16x128_f8f6f4 v[92:95], v[26:33], v[50:57], v[92:95]
	v_mfma_f32_16x16x128_f8f6f4 v[84:87], v[18:25], v[50:57], v[84:87]
	v_mfma_f32_16x16x128_f8f6f4 v[72:75], v[26:33], v[58:65], v[72:75]
	v_mfma_f32_16x16x128_f8f6f4 v[68:71], v[18:25], v[58:65], v[68:71]
	s_setprio 0
	s_setprio 1
	v_mfma_f32_16x16x128_f8f6f4 v[120:123], v[8:15], v[34:41], v[120:123]
	v_mfma_f32_16x16x128_f8f6f4 v[116:119], v[0:7], v[34:41], v[116:119]
	v_mfma_f32_16x16x128_f8f6f4 v[104:107], v[8:15], v[42:49], v[104:107]
	v_mfma_f32_16x16x128_f8f6f4 v[100:103], v[0:7], v[42:49], v[100:103]
	v_mfma_f32_16x16x128_f8f6f4 v[96:99], v[8:15], v[50:57], v[96:99]
	v_mfma_f32_16x16x128_f8f6f4 v[88:91], v[0:7], v[50:57], v[88:91]
	v_mfma_f32_16x16x128_f8f6f4 v[80:83], v[8:15], v[58:65], v[80:83]
	v_mfma_f32_16x16x128_f8f6f4 v[76:79], v[0:7], v[58:65], v[76:79]
	s_setprio 0
	s_barrier
	s_add_i32 s94, s94, 2
	s_add_u32 s60, s60, 0x100
	s_addc_u32 s61, s61, 0
	s_cmp_gt_u32 s94, 5
	s_cbranch_scc1 .LBB0_1122

; #define PG8_STAGE(bufoff, gbase, voff) do { _Pragma("unroll") for (int _i = 0; _i < 2; ++_i) \
;         __builtin_amdgcn_global_load_lds((const unsigned*)((const char*)(gbase) + (voff)[_i]), (PG8_LAS unsigned*)(lds + (bufoff) + ldsw + _i * 8192), 16, 0, 0); } while (0)
; #define PG8_LDA(dst, b, h) do { _Pragma("unroll") for (int m = 0; m < 4; ++m) _Pragma("unroll") for (int k = 0; k < 2; ++k) dst[m][k] = *(const PG8_LAS bf16x8*)(lds + PG8_SA(b, h) + aoff + m * 2048 + k * 1024); } while (0)
; #define PG8_LDB(dst, b, h) do { _Pragma("unroll") for (int n = 0; n < 2; ++n) _Pragma("unroll") for (int k = 0; k < 2; ++k) dst[n][k] = *(const PG8_LAS bf16x8*)(lds + PG8_SB(b, h) + boff + n * 2048 + k * 1024); } while (0)
; #define PG8_WAIT_VR(relax) do { if (relax) asm volatile("s_waitcnt vmcnt(%0)" :: "n"(8 + Epi::NST) : "memory"); else asm volatile("s_waitcnt vmcnt(8)" ::: "memory"); } while (0)
; #define PG8_WAIT_L(n) asm volatile("s_waitcnt lgkmcnt(" #n ")" ::: "memory")
; #define PG8_BAR __builtin_amdgcn_s_barrier()
; #define PG8_SCHED __builtin_amdgcn_sched_barrier(0)
; template <class Epi, class Sched, bool ALIGN_EPI = false, bool SP2 = false, bool F8 = false, bool GATHER = false>
; __device__ __forceinline__ void gemm_phase(PG8_LAS unsigned char* lds, const Gemm g, const Sched& S, const Epi& E, const int tid_in) {
;     ...
;             const char* a1 = cA + (size_t)(t + 1) * kstep;
;             const char* a2 = last ? nA : cA + (size_t)(t + 2) * kstep; const char* b2 = last ? nB : cB + (size_t)(t + 2) * kstep;
;             const char* a3 = a2 + kstep; const char* b3 = b2 + kstep;
;             if (last && has_next) S.a_ready(nxt);
;             const bool relax = SP2 && ALIGN_EPI && t == 0 && ui > 0;
;             if constexpr (SP2) {
;             PG8_LDB(B0, 0, 0); PG8_LDB(B1, 0, 1); PG8_SCHED; PG8_LDA(At, 0, 0); if (!relax) PG8_STAGE(PG8_SA(1, 1), a1 + hstepA, vA1c);
;             PG8_WAIT_VR(relax); PG8_WAIT_L(0); PG8_BAR; PG8_MMA(0, 0, At, B0); PG8_MMA(0, 1, At, B1); PG8_BAR; PG8_SCHED;
;             PG8_LDA(At, 0, 1); PG8_STAGE(PG8_SB(0, 0), b2, voffB); PG8_STAGE(PG8_SB(0, 1), b2 + hstep, voffB); PG8_STAGE(PG8_SA(0, 0), a2, vA0s);
.LBB0_1114:
	s_xor_b64 s[64:65], s[62:63], -1
	s_add_u32 s62, s42, s60
	s_addc_u32 s63, s43, s61
	s_add_u32 s62, s62, 0x100
	s_addc_u32 s63, s63, 0
	s_add_u32 s72, s92, s60
	s_addc_u32 s73, s93, s61
	s_waitcnt lgkmcnt(0)
	s_cmpk_eq_i32 s60, 0x300
	s_cselect_b32 s67, s3, s63
	s_cselect_b32 s66, s49, s62
	s_cselect_b32 s63, s37, s73
	s_cselect_b32 s62, s91, s72
	s_barrier
	s_setprio 1
	s_waitcnt lgkmcnt(0)
	v_mfma_f32_16x16x128_f8f6f4 v[192:195], v[26:33], v[58:65], v[192:195]
	v_mfma_f32_16x16x128_f8f6f4 v[188:191], v[18:25], v[58:65], v[188:191]
	v_mfma_f32_16x16x128_f8f6f4 v[184:187], v[26:33], v[50:57], v[184:187]
	v_mfma_f32_16x16x128_f8f6f4 v[180:183], v[18:25], v[50:57], v[180:183]
	v_mfma_f32_16x16x128_f8f6f4 v[160:163], v[26:33], v[42:49], v[160:163]
	v_mfma_f32_16x16x128_f8f6f4 v[156:159], v[18:25], v[42:49], v[156:159]
	v_mfma_f32_16x16x128_f8f6f4 v[152:155], v[26:33], v[34:41], v[152:155]
	v_mfma_f32_16x16x128_f8f6f4 v[148:151], v[18:25], v[34:41], v[148:151]
	s_setprio 0
	s_setprio 1
	v_mfma_f32_16x16x128_f8f6f4 v[176:179], v[8:15], v[58:65], v[176:179]
	v_mfma_f32_16x16x128_f8f6f4 v[172:175], v[0:7], v[58:65], v[172:175]
	v_mfma_f32_16x16x128_f8f6f4 v[168:171], v[8:15], v[50:57], v[168:171]
	v_mfma_f32_16x16x128_f8f6f4 v[164:167], v[0:7], v[50:57], v[164:167]
	v_mfma_f32_16x16x128_f8f6f4 v[144:147], v[8:15], v[42:49], v[144:147]
	v_mfma_f32_16x16x128_f8f6f4 v[140:143], v[0:7], v[42:49], v[140:143]
	v_mfma_f32_16x16x128_f8f6f4 v[136:139], v[8:15], v[34:41], v[136:139]
	v_mfma_f32_16x16x128_f8f6f4 v[132:135], v[0:7], v[34:41], v[132:135]
	s_setprio 0
	s_barrier
	s_mov_b32 m0, s57
	v_lshl_add_u64 v[218:219], s[62:63], 0, v[204:205]
	s_add_u32 s72, s62, 0x20000
	ds_read_b128 v[58:61], v242 offset:16384
	ds_read_b128 v[62:65], v242 offset:17408
	ds_read_b128 v[50:53], v242 offset:18432
	ds_read_b128 v[54:57], v242 offset:19456
	ds_read_b128 v[42:45], v242 offset:20480
	ds_read_b128 v[46:49], v242 offset:21504
	ds_read_b128 v[34:37], v242 offset:22528
	ds_read_b128 v[38:41], v242 offset:23552
	global_load_lds_dwordx4 v[218:219], off
	v_lshl_add_u64 v[220:221], s[62:63], 0, v[208:209]
	s_mov_b32 m0, s69
	s_addc_u32 s73, s63, 0
	global_load_lds_dwordx4 v[220:221], off
	v_lshl_add_u64 v[196:197], s[72:73], 0, v[204:205]
	s_mov_b32 m0, s78
	v_lshl_add_u64 v[222:223], s[66:67], 0, v[202:203]
	global_load_lds_dwordx4 v[196:197], off
	v_lshl_add_u64 v[196:197], s[72:73], 0, v[208:209]
	s_mov_b32 m0, s79
	v_lshl_add_u64 v[224:225], s[66:67], 0, v[206:207]
	global_load_lds_dwordx4 v[196:197], off
	s_mov_b32 m0, s25
	s_mov_b64 s[72:73], -1
	global_load_lds_dwordx4 v[222:223], off
	s_mov_b32 m0, s80
	s_and_b64 vcc, exec, s[64:65]
	global_load_lds_dwordx4 v[224:225], off
	s_cbranch_vccz .LBB0_1116
	s_waitcnt vmcnt(8)
	s_mov_b64 s[72:73], 0

; #define PG8_STAGE(bufoff, gbase, voff) do { _Pragma("unroll") for (int _i = 0; _i < 2; ++_i) \
;         __builtin_amdgcn_global_load_lds((const unsigned*)((const char*)(gbase) + (voff)[_i]), (PG8_LAS unsigned*)(lds + (bufoff) + ldsw + _i * 8192), 16, 0, 0); } while (0)
; #define PG8_LDA(dst, b, h) do { _Pragma("unroll") for (int m = 0; m < 4; ++m) _Pragma("unroll") for (int k = 0; k < 2; ++k) dst[m][k] = *(const PG8_LAS bf16x8*)(lds + PG8_SA(b, h) + aoff + m * 2048 + k * 1024); } while (0)
; #define PG8_LDB(dst, b, h) do { _Pragma("unroll") for (int n = 0; n < 2; ++n) _Pragma("unroll") for (int k = 0; k < 2; ++k) dst[n][k] = *(const PG8_LAS bf16x8*)(lds + PG8_SB(b, h) + boff + n * 2048 + k * 1024); } while (0)
; #define PG8_WAIT_VR(relax) do { if (relax) asm volatile("s_waitcnt vmcnt(%0)" :: "n"(8 + Epi::NST) : "memory"); else asm volatile("s_waitcnt vmcnt(8)" ::: "memory"); } while (0)
; #define PG8_WAIT_L(n) asm volatile("s_waitcnt lgkmcnt(" #n ")" ::: "memory")
; #define PG8_BAR __builtin_amdgcn_s_barrier()
; #define PG8_SCHED __builtin_amdgcn_sched_barrier(0)
; template <class Epi, class Sched, bool ALIGN_EPI = false, bool SP2 = false, bool F8 = false, bool GATHER = false>
; __device__ __forceinline__ void gemm_phase(PG8_LAS unsigned char* lds, const Gemm g, const Sched& S, const Epi& E, const int tid_in) {
;     ...
;             PG8_WAIT_VR(relax); PG8_WAIT_L(0); PG8_BAR; PG8_MMA(1, 0, At, B0); PG8_MMA(1, 1, At, B1); PG8_BAR; PG8_SCHED;
;             PG8_LDB(B0, 1, 0); PG8_LDB(B1, 1, 1); PG8_SCHED; PG8_LDA(At, 1, 0); PG8_STAGE(PG8_SA(0, 1), a2 + hstepA, vA1s);
.LBB0_1118:
	s_waitcnt lgkmcnt(0)
	s_barrier
	s_setprio 1
	s_waitcnt lgkmcnt(0)
	v_mfma_f32_16x16x128_f8f6f4 v[128:131], v[26:33], v[58:65], v[128:131]
	v_mfma_f32_16x16x128_f8f6f4 v[124:127], v[18:25], v[58:65], v[124:127]
	v_mfma_f32_16x16x128_f8f6f4 v[112:115], v[26:33], v[50:57], v[112:115]
	v_mfma_f32_16x16x128_f8f6f4 v[108:111], v[18:25], v[50:57], v[108:111]
	v_mfma_f32_16x16x128_f8f6f4 v[92:95], v[26:33], v[42:49], v[92:95]
	v_mfma_f32_16x16x128_f8f6f4 v[84:87], v[18:25], v[42:49], v[84:87]
	v_mfma_f32_16x16x128_f8f6f4 v[72:75], v[26:33], v[34:41], v[72:75]
	v_mfma_f32_16x16x128_f8f6f4 v[68:71], v[18:25], v[34:41], v[68:71]
	s_setprio 0
	s_setprio 1
	v_mfma_f32_16x16x128_f8f6f4 v[120:123], v[8:15], v[58:65], v[120:123]
	v_mfma_f32_16x16x128_f8f6f4 v[116:119], v[0:7], v[58:65], v[116:119]
	v_mfma_f32_16x16x128_f8f6f4 v[104:107], v[8:15], v[50:57], v[104:107]
	v_mfma_f32_16x16x128_f8f6f4 v[100:103], v[0:7], v[50:57], v[100:103]
	v_mfma_f32_16x16x128_f8f6f4 v[96:99], v[8:15], v[42:49], v[96:99]
	v_mfma_f32_16x16x128_f8f6f4 v[88:91], v[0:7], v[42:49], v[88:91]
	v_mfma_f32_16x16x128_f8f6f4 v[80:83], v[8:15], v[34:41], v[80:83]
	v_mfma_f32_16x16x128_f8f6f4 v[76:79], v[0:7], v[34:41], v[76:79]
	s_setprio 0
	s_barrier
	v_add_u32_e32 v0, 0x18000, v234
	v_add_u32_e32 v4, 0x1c000, v234
	ds_read_b128 v[26:29], v0
	ds_read_b128 v[30:33], v0 offset:1024
	ds_read_b128 v[18:21], v0 offset:2048
	ds_read_b128 v[22:25], v0 offset:3072
	ds_read_b128 v[8:11], v4
	ds_read_b128 v[12:15], v4 offset:1024
	ds_read_b128 v[0:3], v4 offset:2048
	ds_read_b128 v[4:7], v4 offset:3072
	s_add_u32 s66, s66, 0x20000
	s_addc_u32 s67, s67, 0
	s_mov_b32 m0, s81
	v_lshl_add_u64 v[196:197], s[66:67], 0, v[202:203]
	ds_read_b128 v[58:61], v242 offset:32768
	ds_read_b128 v[62:65], v242 offset:33792
	ds_read_b128 v[50:53], v242 offset:34816
	ds_read_b128 v[54:57], v242 offset:35840
	ds_read_b128 v[42:45], v242 offset:36864
	ds_read_b128 v[46:49], v242 offset:37888
	ds_read_b128 v[34:37], v242 offset:38912
	ds_read_b128 v[38:41], v242 offset:39936
	global_load_lds_dwordx4 v[196:197], off
	v_lshl_add_u64 v[196:197], s[66:67], 0, v[206:207]
	s_mov_b32 m0, s82
	s_mov_b64 s[66:67], -1
	global_load_lds_dwordx4 v[196:197], off
	s_and_b64 vcc, exec, s[64:65]
	s_cbranch_vccz .LBB0_1120
	s_waitcnt vmcnt(8)
	s_mov_b64 s[66:67], 0
